# norm phase: x rows loaded straight into ring slots, one counted vmcnt per row instead of drain-after-request
# speedup vs baseline: 1.0170x; 1.0083x over previous
; __device__ __forceinline__ void norm_phase(int upd_l, int upd_s, int h_l, int h_s, int xsrc, int xdst, bool dummy, int vc) {
;     ...
;         for (int row = rbeg; row < rend; row += 4 * rstep) {
;             if (row + 3 * rstep < rend) NP_LOAD(row + 3 * rstep, v3, xb3, yb3);
;             NP_PROC(row, v0, xb0, yb0);
.LBB0_277:
	v_lshl_add_u64 v[198:199], v[94:95], 0, v[206:207]
	global_load_dwordx2 v[188:189], v[198:199], off
	global_load_dwordx2 v[186:187], v[198:199], off offset:512
	global_load_dwordx2 v[184:185], v[198:199], off offset:1024
	global_load_dwordx2 v[182:183], v[198:199], off offset:1536
.LBB0_278:
.LBB0_279:
	s_or_b64 exec, exec, s[30:31]
	s_or_b64 vcc, s[42:43], s[44:45]
	s_cbranch_vccnz .Lnp_w12_0
	s_waitcnt vmcnt(24)
	s_branch .Lnp_wd_0
.Lnp_w12_0:
	s_waitcnt vmcnt(12)
.Lnp_wd_0:
	v_cndmask_b32_e64 v0, 0, 1, s[6:7]
	v_cmp_ne_u32_e64 s[48:49], 1, v0
	s_andn2_b64 vcc, exec, s[6:7]
	s_cbranch_vccnz .LBB0_281
	v_cvt_f32_f16_sdwa v37, v134 dst_sel:DWORD dst_unused:UNUSED_PAD src0_sel:WORD_1
	v_cvt_f32_f16_e32 v36, v134
	v_cvt_f32_f16_sdwa v39, v135 dst_sel:DWORD dst_unused:UNUSED_PAD src0_sel:WORD_1
	v_cvt_f32_f16_e32 v38, v135
	v_cvt_f32_f16_sdwa v41, v136 dst_sel:DWORD dst_unused:UNUSED_PAD src0_sel:WORD_1
	v_cvt_f32_f16_e32 v40, v136
	v_cvt_f32_f16_sdwa v43, v137 dst_sel:DWORD dst_unused:UNUSED_PAD src0_sel:WORD_1
	v_cvt_f32_f16_e32 v42, v137
	v_cvt_f32_f16_sdwa v45, v138 dst_sel:DWORD dst_unused:UNUSED_PAD src0_sel:WORD_1
	v_cvt_f32_f16_e32 v44, v138
	v_cvt_f32_f16_sdwa v47, v139 dst_sel:DWORD dst_unused:UNUSED_PAD src0_sel:WORD_1
	v_cvt_f32_f16_e32 v46, v139
	v_cvt_f32_f16_sdwa v49, v140 dst_sel:DWORD dst_unused:UNUSED_PAD src0_sel:WORD_1
	v_cvt_f32_f16_e32 v48, v140
	v_cvt_f32_f16_sdwa v51, v141 dst_sel:DWORD dst_unused:UNUSED_PAD src0_sel:WORD_1
	v_cvt_f32_f16_e32 v50, v141
.LBB0_281:
	s_and_b64 vcc, exec, s[42:43]
	s_cbranch_vccnz .LBB0_286
	v_and_b32_e32 v201, 0xffff0000, v133
	v_and_b32_e32 v200, 0xffff0000, v132
	v_and_b32_e32 v207, 0xffff0000, v143
	v_and_b32_e32 v206, 0xffff0000, v142
	v_lshlrev_b32_e32 v199, 16, v133
	v_lshlrev_b32_e32 v198, 16, v132
	v_pk_mul_f32 v[202:203], v[200:201], v[200:201]
	v_lshlrev_b32_e32 v205, 16, v143
	v_lshlrev_b32_e32 v204, 16, v142
	v_pk_mul_f32 v[208:209], v[206:207], v[206:207]
	v_lshlrev_b32_e32 v216, 16, v144
	v_and_b32_e32 v217, 0xffff0000, v144
	v_lshlrev_b32_e32 v228, 16, v145
	v_lshlrev_b32_e32 v220, 16, v146
	v_pk_fma_f32 v[202:203], v[198:199], v[198:199], v[202:203]
	v_pk_fma_f32 v[208:209], v[204:205], v[204:205], v[208:209]
	v_mul_f32_e32 v221, v216, v216
	v_mul_f32_e32 v225, v217, v217
	v_and_b32_e32 v229, 0xffff0000, v145
	v_mul_f32_e32 v0, v228, v228
	v_mov_b32_e32 v224, v220
	v_pk_add_f32 v[202:203], v[202:203], v[202:203] op_sel_hi:[0,1]
	v_pk_add_f32 v[208:209], v[208:209], v[208:209] op_sel_hi:[0,1]
	v_pk_fma_f32 v[230:231], v[228:229], v[228:229], v[0:1] op_sel_hi:[1,1,0]
	v_and_b32_e32 v179, 0xffff0000, v146
	v_lshlrev_b32_e32 v238, 16, v147
	v_and_b32_e32 v239, 0xffff0000, v147
	v_pk_add_f32 v[224:225], v[220:221], v[224:225]
	v_mul_f32_e32 v230, v179, v179
	v_mul_f32_e32 v208, v238, v238
	v_mul_f32_e32 v202, v239, v239
	v_mul_f32_e32 v242, v220, v220
	v_mov_b32_e32 v243, v225
	v_pk_add_f32 v[224:225], v[242:243], v[230:231]
	v_pk_add_f32 v[202:203], v[208:209], v[202:203]
	v_mov_b32_e32 v221, v179
	v_pk_add_f32 v[202:203], v[224:225], v[202:203]
	s_nop 0
	v_add_f32_e32 v0, v202, v203
	v_mov_b32_e32 v202, 0
	v_mov_b32_e32 v203, v200
	v_add_f32_dpp v0, v0, v0 quad_perm:[1,0,3,2] row_mask:0xf bank_mask:0xf bound_ctrl:1
	v_mov_b32_e32 v200, v199
	s_nop 0
	v_add_f32_dpp v0, v0, v0 quad_perm:[2,3,0,1] row_mask:0xf bank_mask:0xf bound_ctrl:1
	s_nop 1
	v_add_f32_dpp v0, v0, v0 row_half_mirror row_mask:0xf bank_mask:0xf bound_ctrl:1
	s_nop 1
	v_add_f32_dpp v0, v0, v0 row_mirror row_mask:0xf bank_mask:0xf bound_ctrl:1
	s_nop 1
	v_mov_b32_dpp v202, v0 row_bcast:15 row_mask:0xa bank_mask:0xf
	v_add_f32_e32 v0, v0, v202
	v_mov_b32_e32 v202, 0
	s_nop 1
	v_mov_b32_dpp v202, v0 row_bcast:31 row_mask:0xc bank_mask:0xf
	v_add_f32_e32 v0, v0, v202
	s_nop 0
	v_readlane_b32 s2, v0, 63
	s_nop 1
	v_fma_f32 v0, s2, v235, v215
	v_mul_f32_e32 v202, 0x4b800000, v0
	v_cmp_gt_f32_e32 vcc, s15, v0
	s_mov_b64 s[2:3], -1
	s_nop 0
	v_cndmask_b32_e32 v0, v0, v202, vcc
	v_rsq_f32_e32 v0, v0
	s_nop 0
	v_mul_f32_e32 v202, 0x45800000, v0
	v_cndmask_b32_e32 v0, v0, v202, vcc
	v_mov_b32_e32 v202, v198
	v_pk_mul_f32 v[198:199], v[108:109], v[200:201]
	v_pk_mul_f32 v[202:203], v[104:105], v[202:203]
	v_pk_fma_f32 v[38:39], v[198:199], v[0:1], v[38:39] op_sel_hi:[1,0,1]
	v_mov_b32_e32 v198, v204
	v_mov_b32_e32 v199, v206
	v_mov_b32_e32 v206, v205
	v_pk_mul_f32 v[198:199], v[100:101], v[198:199]
	v_pk_mul_f32 v[200:201], v[102:103], v[206:207]
	v_pk_fma_f32 v[40:41], v[198:199], v[0:1], v[40:41] op_sel_hi:[1,0,1]
	v_pk_fma_f32 v[42:43], v[200:201], v[0:1], v[42:43] op_sel_hi:[1,0,1]
	v_pk_mul_f32 v[198:199], v[106:107], v[216:217]
	v_pk_mul_f32 v[200:201], v[110:111], v[228:229]
	v_pk_fma_f32 v[44:45], v[198:199], v[0:1], v[44:45] op_sel_hi:[1,0,1]
	v_pk_fma_f32 v[46:47], v[200:201], v[0:1], v[46:47] op_sel_hi:[1,0,1]
	v_pk_mul_f32 v[198:199], v[114:115], v[220:221]
	v_pk_mul_f32 v[200:201], v[112:113], v[238:239]
	v_pk_fma_f32 v[36:37], v[202:203], v[0:1], v[36:37] op_sel_hi:[1,0,1]
	v_pk_fma_f32 v[50:51], v[200:201], v[0:1], v[50:51] op_sel_hi:[1,0,1]
	v_pk_fma_f32 v[48:49], v[198:199], v[0:1], v[48:49] op_sel_hi:[1,0,1]
	s_and_b64 vcc, exec, s[8:9]
	s_cbranch_vccz .LBB0_284
	v_ashrrev_i32_e32 v179, 31, v178
	v_lshlrev_b64 v[198:199], 11, v[178:179]
	v_lshl_add_u64 v[198:199], v[96:97], 0, v[198:199]
	v_cvt_pk_f16_f32 v200, v36, v37
	v_cvt_pk_f16_f32 v201, v38, v39
	global_store_dwordx2 v[198:199], v[200:201], off
	v_cvt_pk_f16_f32 v200, v40, v41
	v_cvt_pk_f16_f32 v201, v42, v43
	global_store_dwordx2 v[198:199], v[200:201], off offset:512
	v_cvt_pk_f16_f32 v200, v44, v45
	v_cvt_pk_f16_f32 v201, v46, v47
	global_store_dwordx2 v[198:199], v[200:201], off offset:1024
	v_cvt_pk_f16_f32 v200, v48, v49
	v_cvt_pk_f16_f32 v201, v50, v51
	global_store_dwordx2 v[198:199], v[200:201], off offset:1536
	s_mov_b64 s[2:3], 0

.LBB0_286:
	s_and_b64 vcc, exec, s[44:45]
	s_cbranch_vccnz .LBB0_288
	v_pk_mul_f32 v[202:203], v[38:39], v[38:39]
	v_pk_mul_f32 v[204:205], v[36:37], v[36:37]
	v_pk_mul_f32 v[198:199], v[42:43], v[42:43]
	v_pk_mul_f32 v[200:201], v[40:41], v[40:41]
	v_pk_mov_b32 v[206:207], v[204:205], v[202:203] op_sel:[1,0]
	v_mov_b32_e32 v205, v203
	v_pk_add_f32 v[202:203], v[206:207], v[204:205]
	v_pk_mov_b32 v[204:205], v[200:201], v[198:199] op_sel:[1,0]
	v_mov_b32_e32 v201, v199
	v_mul_f32_e32 v0, v44, v44
	v_pk_add_f32 v[198:199], v[204:205], v[200:201]
	v_pk_fma_f32 v[200:201], v[44:45], v[44:45], v[0:1] op_sel_hi:[1,1,0]
	v_mul_f32_e32 v0, v46, v46
	v_pk_add_f32 v[202:203], v[202:203], v[202:203] op_sel_hi:[0,1]
	v_pk_add_f32 v[198:199], v[198:199], v[198:199] op_sel_hi:[0,1]
	v_pk_fma_f32 v[204:205], v[46:47], v[46:47], v[0:1] op_sel_hi:[1,1,0]
	v_mul_f32_e32 v200, v48, v48
	v_mul_f32_e32 v204, v49, v49
	v_mul_f32_e32 v202, v50, v50
	v_mul_f32_e32 v198, v51, v51
	v_pk_add_f32 v[200:201], v[200:201], v[204:205]
	v_pk_add_f32 v[198:199], v[202:203], v[198:199]
	v_mov_b32_e32 v179, 0
	v_pk_add_f32 v[198:199], v[200:201], v[198:199]
	s_nop 0
	v_add_f32_e32 v0, v198, v199
	s_nop 1
	v_add_f32_dpp v0, v0, v0 quad_perm:[1,0,3,2] row_mask:0xf bank_mask:0xf bound_ctrl:1
	s_nop 1
	v_add_f32_dpp v0, v0, v0 quad_perm:[2,3,0,1] row_mask:0xf bank_mask:0xf bound_ctrl:1
	s_nop 1
	v_add_f32_dpp v0, v0, v0 row_half_mirror row_mask:0xf bank_mask:0xf bound_ctrl:1
	s_nop 1
	v_add_f32_dpp v0, v0, v0 row_mirror row_mask:0xf bank_mask:0xf bound_ctrl:1
	s_nop 1
	v_mov_b32_dpp v179, v0 row_bcast:15 row_mask:0xa bank_mask:0xf
	v_add_f32_e32 v0, v0, v179
	v_mov_b32_e32 v179, 0
	s_nop 1
	v_mov_b32_dpp v179, v0 row_bcast:31 row_mask:0xc bank_mask:0xf
	v_add_f32_e32 v0, v0, v179
	s_nop 0
	v_readlane_b32 s2, v0, 63
	s_nop 1
	v_fma_f32 v0, s2, v235, v215
	v_mul_f32_e32 v179, 0x4b800000, v0
	v_cmp_gt_f32_e32 vcc, s15, v0
	s_nop 1
	v_cndmask_b32_e32 v0, v0, v179, vcc
	v_rsq_f32_e32 v0, v0
	s_nop 0
	v_mul_f32_e32 v179, 0x45800000, v0
	v_cndmask_b32_e32 v0, v0, v179, vcc
	v_ashrrev_i32_e32 v179, 31, v178
	v_pk_mul_f32 v[200:201], v[36:37], v[0:1] op_sel_hi:[1,0]
	v_lshlrev_b64 v[198:199], 11, v[178:179]
	v_pk_mul_f32 v[202:203], v[38:39], v[0:1] op_sel_hi:[1,0]
	v_pk_fma_f32 v[200:201], v[120:121], v[200:201], v[20:21]
	v_lshl_add_u64 v[198:199], v[94:95], 0, v[198:199]
	v_pk_fma_f32 v[202:203], v[124:125], v[202:203], v[22:23]
	v_cvt_pk_bf16_f32 v200, v200, v201
	s_nop 0
	v_cvt_pk_bf16_f32 v201, v202, v203
	global_store_dwordx2 v[198:199], v[200:201], off
	v_pk_mul_f32 v[200:201], v[40:41], v[0:1] op_sel_hi:[1,0]
	v_pk_mul_f32 v[202:203], v[42:43], v[0:1] op_sel_hi:[1,0]
	v_pk_fma_f32 v[200:201], v[116:117], v[200:201], v[24:25]
	v_pk_fma_f32 v[202:203], v[118:119], v[202:203], v[26:27]
	v_cvt_pk_bf16_f32 v200, v200, v201
	s_nop 0
	v_cvt_pk_bf16_f32 v201, v202, v203
	global_store_dwordx2 v[198:199], v[200:201], off offset:512
	v_pk_mul_f32 v[200:201], v[44:45], v[0:1] op_sel_hi:[1,0]
	v_pk_mul_f32 v[202:203], v[46:47], v[0:1] op_sel_hi:[1,0]
	v_pk_fma_f32 v[200:201], v[122:123], v[200:201], v[28:29]
	v_pk_fma_f32 v[202:203], v[126:127], v[202:203], v[30:31]
	v_cvt_pk_bf16_f32 v200, v200, v201
	s_nop 0
	v_cvt_pk_bf16_f32 v201, v202, v203
	global_store_dwordx2 v[198:199], v[200:201], off offset:1024
	v_pk_mul_f32 v[200:201], v[48:49], v[0:1] op_sel_hi:[1,0]
	v_pk_mul_f32 v[202:203], v[50:51], v[0:1] op_sel_hi:[1,0]
	v_pk_fma_f32 v[200:201], v[130:131], v[200:201], v[32:33]
	v_pk_fma_f32 v[202:203], v[128:129], v[202:203], v[34:35]
	v_cvt_pk_bf16_f32 v200, v200, v201
	s_nop 0
	v_cvt_pk_bf16_f32 v201, v202, v203
	global_store_dwordx2 v[198:199], v[200:201], off offset:1536

; __device__ __forceinline__ void norm_phase(int upd_l, int upd_s, int h_l, int h_s, int xsrc, int xdst, bool dummy, int vc) {
;     ...
;             if (row + 4 * rstep < rend) NP_LOAD(row + 4 * rstep, v0, xb0, yb0);
;             if (row + rstep < rend) NP_PROC(row + rstep, v1, xb1, yb1);
.LBB0_292:
	v_lshl_add_u64 v[198:199], v[94:95], 0, v[206:207]
	global_load_dwordx2 v[132:133], v[198:199], off
	global_load_dwordx2 v[142:143], v[198:199], off offset:512
	global_load_dwordx2 v[144:145], v[198:199], off offset:1024
	global_load_dwordx2 v[146:147], v[198:199], off offset:1536
.LBB0_293:
.LBB0_294:
	s_or_b64 exec, exec, s[30:31]
	v_add_u32_e32 v198, s33, v178
	v_cmp_lt_i32_e32 vcc, v198, v212
	s_and_saveexec_b64 s[30:31], vcc
	s_cbranch_execz .LBB0_304
	s_or_b64 vcc, s[42:43], s[44:45]
	s_cbranch_vccnz .Lnp_w12_1
	s_waitcnt vmcnt(24)
	s_branch .Lnp_wd_1

.Lnp_wd_1:
	s_and_b64 vcc, exec, s[48:49]
	s_cbranch_vccnz .LBB0_297
	v_cvt_f32_f16_sdwa v5, v148 dst_sel:DWORD dst_unused:UNUSED_PAD src0_sel:WORD_1
	v_cvt_f32_f16_e32 v4, v148
	v_cvt_f32_f16_sdwa v7, v149 dst_sel:DWORD dst_unused:UNUSED_PAD src0_sel:WORD_1
	v_cvt_f32_f16_e32 v6, v149
	v_cvt_f32_f16_sdwa v9, v150 dst_sel:DWORD dst_unused:UNUSED_PAD src0_sel:WORD_1
	v_cvt_f32_f16_e32 v8, v150
	v_cvt_f32_f16_sdwa v11, v151 dst_sel:DWORD dst_unused:UNUSED_PAD src0_sel:WORD_1
	v_cvt_f32_f16_e32 v10, v151
	v_cvt_f32_f16_sdwa v13, v152 dst_sel:DWORD dst_unused:UNUSED_PAD src0_sel:WORD_1
	v_cvt_f32_f16_e32 v12, v152
	v_cvt_f32_f16_sdwa v15, v153 dst_sel:DWORD dst_unused:UNUSED_PAD src0_sel:WORD_1
	v_cvt_f32_f16_e32 v14, v153
	v_cvt_f32_f16_sdwa v17, v156 dst_sel:DWORD dst_unused:UNUSED_PAD src0_sel:WORD_1
	v_cvt_f32_f16_e32 v16, v156
	v_cvt_f32_f16_sdwa v19, v157 dst_sel:DWORD dst_unused:UNUSED_PAD src0_sel:WORD_1
	v_cvt_f32_f16_e32 v18, v157
.LBB0_297:
	s_and_b64 vcc, exec, s[42:43]
	s_cbranch_vccnz .LBB0_302
	v_and_b32_e32 v203, 0xffff0000, v155
	v_and_b32_e32 v202, 0xffff0000, v154
	v_and_b32_e32 v209, 0xffff0000, v159
	v_and_b32_e32 v208, 0xffff0000, v158
	v_lshlrev_b32_e32 v201, 16, v155
	v_lshlrev_b32_e32 v200, 16, v154
	v_pk_mul_f32 v[204:205], v[202:203], v[202:203]
	v_lshlrev_b32_e32 v207, 16, v159
	v_lshlrev_b32_e32 v206, 16, v158
	v_pk_mul_f32 v[216:217], v[208:209], v[208:209]
	v_lshlrev_b32_e32 v220, 16, v160
	v_and_b32_e32 v221, 0xffff0000, v160
	v_lshlrev_b32_e32 v230, 16, v161
	v_lshlrev_b32_e32 v224, 16, v162
	v_pk_fma_f32 v[204:205], v[200:201], v[200:201], v[204:205]
	v_pk_fma_f32 v[216:217], v[206:207], v[206:207], v[216:217]
	v_mul_f32_e32 v225, v220, v220
	v_mul_f32_e32 v229, v221, v221
	v_and_b32_e32 v231, 0xffff0000, v161
	v_mul_f32_e32 v0, v230, v230
	v_mov_b32_e32 v228, v224
	v_pk_add_f32 v[204:205], v[204:205], v[204:205] op_sel_hi:[0,1]
	v_pk_add_f32 v[216:217], v[216:217], v[216:217] op_sel_hi:[0,1]
	v_pk_fma_f32 v[238:239], v[230:231], v[230:231], v[0:1] op_sel_hi:[1,1,0]
	v_and_b32_e32 v179, 0xffff0000, v162
	v_lshlrev_b32_e32 v242, 16, v163
	v_and_b32_e32 v243, 0xffff0000, v163
	v_pk_add_f32 v[228:229], v[224:225], v[228:229]
	v_mul_f32_e32 v238, v179, v179
	v_mul_f32_e32 v216, v242, v242
	v_mul_f32_e32 v204, v243, v243
	v_mul_f32_e32 v244, v224, v224
	v_mov_b32_e32 v245, v229
	v_pk_add_f32 v[228:229], v[244:245], v[238:239]
	v_pk_add_f32 v[204:205], v[216:217], v[204:205]
	v_mov_b32_e32 v199, 0
	v_pk_add_f32 v[204:205], v[228:229], v[204:205]
	v_mov_b32_e32 v225, v179
	v_add_f32_e32 v0, v204, v205
	v_mov_b32_e32 v205, v202
	v_mov_b32_e32 v202, v201
	v_add_f32_dpp v0, v0, v0 quad_perm:[1,0,3,2] row_mask:0xf bank_mask:0xf bound_ctrl:1
	v_mov_b32_e32 v204, v200
	v_pk_mul_f32 v[200:201], v[108:109], v[202:203]
	v_add_f32_dpp v0, v0, v0 quad_perm:[2,3,0,1] row_mask:0xf bank_mask:0xf bound_ctrl:1
	v_pk_mul_f32 v[204:205], v[104:105], v[204:205]
	s_nop 0
	v_add_f32_dpp v0, v0, v0 row_half_mirror row_mask:0xf bank_mask:0xf bound_ctrl:1
	s_nop 1
	v_add_f32_dpp v0, v0, v0 row_mirror row_mask:0xf bank_mask:0xf bound_ctrl:1
	s_nop 1
	v_mov_b32_dpp v199, v0 row_bcast:15 row_mask:0xa bank_mask:0xf
	v_add_f32_e32 v0, v0, v199
	v_mov_b32_e32 v199, 0
	s_nop 1
	v_mov_b32_dpp v199, v0 row_bcast:31 row_mask:0xc bank_mask:0xf
	v_add_f32_e32 v0, v0, v199
	s_nop 0
	v_readlane_b32 s2, v0, 63
	s_nop 1
	v_fma_f32 v0, s2, v235, v215
	v_mul_f32_e32 v199, 0x4b800000, v0
	v_cmp_gt_f32_e32 vcc, s15, v0
	s_mov_b64 s[2:3], -1
	s_nop 0
	v_cndmask_b32_e32 v0, v0, v199, vcc
	v_rsq_f32_e32 v0, v0
	s_nop 0
	v_mul_f32_e32 v199, 0x45800000, v0
	v_cndmask_b32_e32 v0, v0, v199, vcc
	v_pk_fma_f32 v[6:7], v[200:201], v[0:1], v[6:7] op_sel_hi:[1,0,1]
	v_mov_b32_e32 v200, v206
	v_mov_b32_e32 v201, v208
	v_mov_b32_e32 v208, v207
	v_pk_mul_f32 v[200:201], v[100:101], v[200:201]
	v_pk_mul_f32 v[202:203], v[102:103], v[208:209]
	v_pk_fma_f32 v[8:9], v[200:201], v[0:1], v[8:9] op_sel_hi:[1,0,1]
	v_pk_fma_f32 v[10:11], v[202:203], v[0:1], v[10:11] op_sel_hi:[1,0,1]
	v_pk_mul_f32 v[200:201], v[106:107], v[220:221]
	v_pk_mul_f32 v[202:203], v[110:111], v[230:231]
	v_pk_fma_f32 v[12:13], v[200:201], v[0:1], v[12:13] op_sel_hi:[1,0,1]
	v_pk_fma_f32 v[14:15], v[202:203], v[0:1], v[14:15] op_sel_hi:[1,0,1]
	v_pk_mul_f32 v[200:201], v[114:115], v[224:225]
	v_pk_mul_f32 v[202:203], v[112:113], v[242:243]
	v_pk_fma_f32 v[4:5], v[204:205], v[0:1], v[4:5] op_sel_hi:[1,0,1]
	v_pk_fma_f32 v[18:19], v[202:203], v[0:1], v[18:19] op_sel_hi:[1,0,1]
	v_pk_fma_f32 v[16:17], v[200:201], v[0:1], v[16:17] op_sel_hi:[1,0,1]
	s_and_b64 vcc, exec, s[8:9]
	s_cbranch_vccz .LBB0_300
	v_ashrrev_i32_e32 v199, 31, v198
	v_lshlrev_b64 v[200:201], 11, v[198:199]
	v_lshl_add_u64 v[200:201], v[96:97], 0, v[200:201]
	v_cvt_pk_f16_f32 v202, v4, v5
	v_cvt_pk_f16_f32 v203, v6, v7
	global_store_dwordx2 v[200:201], v[202:203], off
	v_cvt_pk_f16_f32 v202, v8, v9
	v_cvt_pk_f16_f32 v203, v10, v11
	global_store_dwordx2 v[200:201], v[202:203], off offset:512
	v_cvt_pk_f16_f32 v202, v12, v13
	v_cvt_pk_f16_f32 v203, v14, v15
	global_store_dwordx2 v[200:201], v[202:203], off offset:1024
	v_cvt_pk_f16_f32 v202, v16, v17
	v_cvt_pk_f16_f32 v203, v18, v19
	global_store_dwordx2 v[200:201], v[202:203], off offset:1536
	s_mov_b64 s[2:3], 0

.LBB0_302:
	s_and_b64 vcc, exec, s[44:45]
	s_cbranch_vccnz .LBB0_304
	v_pk_mul_f32 v[204:205], v[6:7], v[6:7]
	v_pk_mul_f32 v[206:207], v[4:5], v[4:5]
	v_pk_mul_f32 v[200:201], v[10:11], v[10:11]
	v_pk_mul_f32 v[202:203], v[8:9], v[8:9]
	v_pk_mov_b32 v[208:209], v[206:207], v[204:205] op_sel:[1,0]
	v_mov_b32_e32 v207, v205
	v_pk_add_f32 v[204:205], v[208:209], v[206:207]
	v_pk_mov_b32 v[206:207], v[202:203], v[200:201] op_sel:[1,0]
	v_mov_b32_e32 v203, v201
	v_mul_f32_e32 v0, v12, v12
	v_pk_add_f32 v[200:201], v[206:207], v[202:203]
	v_pk_fma_f32 v[202:203], v[12:13], v[12:13], v[0:1] op_sel_hi:[1,1,0]
	v_mul_f32_e32 v0, v14, v14
	v_pk_add_f32 v[204:205], v[204:205], v[204:205] op_sel_hi:[0,1]
	v_pk_add_f32 v[200:201], v[200:201], v[200:201] op_sel_hi:[0,1]
	v_pk_fma_f32 v[206:207], v[14:15], v[14:15], v[0:1] op_sel_hi:[1,1,0]
	v_mul_f32_e32 v202, v16, v16
	v_mul_f32_e32 v206, v17, v17
	v_mul_f32_e32 v204, v18, v18
	v_mul_f32_e32 v200, v19, v19
	v_pk_add_f32 v[202:203], v[202:203], v[206:207]
	v_pk_add_f32 v[200:201], v[204:205], v[200:201]
	v_mov_b32_e32 v179, 0
	v_pk_add_f32 v[200:201], v[202:203], v[200:201]
	v_ashrrev_i32_e32 v199, 31, v198
	v_add_f32_e32 v0, v200, v201
	v_lshlrev_b64 v[198:199], 11, v[198:199]
	v_lshl_add_u64 v[198:199], v[94:95], 0, v[198:199]
	v_add_f32_dpp v0, v0, v0 quad_perm:[1,0,3,2] row_mask:0xf bank_mask:0xf bound_ctrl:1
	s_nop 1
	v_add_f32_dpp v0, v0, v0 quad_perm:[2,3,0,1] row_mask:0xf bank_mask:0xf bound_ctrl:1
	s_nop 1
	v_add_f32_dpp v0, v0, v0 row_half_mirror row_mask:0xf bank_mask:0xf bound_ctrl:1
	s_nop 1
	v_add_f32_dpp v0, v0, v0 row_mirror row_mask:0xf bank_mask:0xf bound_ctrl:1
	s_nop 1
	v_mov_b32_dpp v179, v0 row_bcast:15 row_mask:0xa bank_mask:0xf
	v_add_f32_e32 v0, v0, v179
	v_mov_b32_e32 v179, 0
	s_nop 1
	v_mov_b32_dpp v179, v0 row_bcast:31 row_mask:0xc bank_mask:0xf
	v_add_f32_e32 v0, v0, v179
	s_nop 0
	v_readlane_b32 s2, v0, 63
	s_nop 1
	v_fma_f32 v0, s2, v235, v215
	v_mul_f32_e32 v179, 0x4b800000, v0
	v_cmp_gt_f32_e32 vcc, s15, v0
	s_nop 1
	v_cndmask_b32_e32 v0, v0, v179, vcc
	v_rsq_f32_e32 v0, v0
	s_nop 0
	v_mul_f32_e32 v179, 0x45800000, v0
	v_cndmask_b32_e32 v0, v0, v179, vcc
	v_pk_mul_f32 v[200:201], v[4:5], v[0:1] op_sel_hi:[1,0]
	v_pk_mul_f32 v[202:203], v[6:7], v[0:1] op_sel_hi:[1,0]
	v_pk_fma_f32 v[200:201], v[120:121], v[200:201], v[20:21]
	v_pk_fma_f32 v[202:203], v[124:125], v[202:203], v[22:23]
	v_cvt_pk_bf16_f32 v200, v200, v201
	s_nop 0
	v_cvt_pk_bf16_f32 v201, v202, v203
	global_store_dwordx2 v[198:199], v[200:201], off
	v_pk_mul_f32 v[200:201], v[8:9], v[0:1] op_sel_hi:[1,0]
	v_pk_mul_f32 v[202:203], v[10:11], v[0:1] op_sel_hi:[1,0]
	v_pk_fma_f32 v[200:201], v[116:117], v[200:201], v[24:25]
	v_pk_fma_f32 v[202:203], v[118:119], v[202:203], v[26:27]
	v_cvt_pk_bf16_f32 v200, v200, v201
	s_nop 0
	v_cvt_pk_bf16_f32 v201, v202, v203
	global_store_dwordx2 v[198:199], v[200:201], off offset:512
	v_pk_mul_f32 v[200:201], v[12:13], v[0:1] op_sel_hi:[1,0]
	v_pk_mul_f32 v[202:203], v[14:15], v[0:1] op_sel_hi:[1,0]
	v_pk_fma_f32 v[200:201], v[122:123], v[200:201], v[28:29]
	v_pk_fma_f32 v[202:203], v[126:127], v[202:203], v[30:31]
	v_cvt_pk_bf16_f32 v200, v200, v201
	s_nop 0
	v_cvt_pk_bf16_f32 v201, v202, v203
	global_store_dwordx2 v[198:199], v[200:201], off offset:1024
	v_pk_mul_f32 v[200:201], v[16:17], v[0:1] op_sel_hi:[1,0]
	v_pk_mul_f32 v[202:203], v[18:19], v[0:1] op_sel_hi:[1,0]
	v_pk_fma_f32 v[200:201], v[130:131], v[200:201], v[32:33]
	v_pk_fma_f32 v[202:203], v[128:129], v[202:203], v[34:35]
	v_cvt_pk_bf16_f32 v200, v200, v201
	s_nop 0
	v_cvt_pk_bf16_f32 v201, v202, v203
	global_store_dwordx2 v[198:199], v[200:201], off offset:1536

; __device__ __forceinline__ void norm_phase(int upd_l, int upd_s, int h_l, int h_s, int xsrc, int xdst, bool dummy, int vc) {
;     ...
;             if (row + 5 * rstep < rend) NP_LOAD(row + 5 * rstep, v1, xb1, yb1);
;             if (row + 2 * rstep < rend) NP_PROC(row + 2 * rstep, v2, xb2, yb2);
.LBB0_308:
	v_lshl_add_u64 v[200:201], v[94:95], 0, v[198:199]
	global_load_dwordx2 v[154:155], v[200:201], off
	global_load_dwordx2 v[158:159], v[200:201], off offset:512
	global_load_dwordx2 v[160:161], v[200:201], off offset:1024
	global_load_dwordx2 v[162:163], v[200:201], off offset:1536
.LBB0_309:
.LBB0_310:
	s_or_b64 exec, exec, s[30:31]
	v_add_u32_e32 v198, s92, v178
	v_cmp_lt_i32_e32 vcc, v198, v212
	s_and_saveexec_b64 s[30:31], vcc
	s_cbranch_execz .LBB0_320
	s_or_b64 vcc, s[42:43], s[44:45]
	s_cbranch_vccnz .Lnp_w12_2
	s_waitcnt vmcnt(24)
	s_branch .Lnp_wd_2

.Lnp_wd_2:
	s_and_b64 vcc, exec, s[48:49]
	s_cbranch_vccnz .LBB0_313
	v_cvt_f32_f16_sdwa v53, v164 dst_sel:DWORD dst_unused:UNUSED_PAD src0_sel:WORD_1
	v_cvt_f32_f16_e32 v52, v164
	v_cvt_f32_f16_sdwa v55, v165 dst_sel:DWORD dst_unused:UNUSED_PAD src0_sel:WORD_1
	v_cvt_f32_f16_e32 v54, v165
	v_cvt_f32_f16_sdwa v57, v166 dst_sel:DWORD dst_unused:UNUSED_PAD src0_sel:WORD_1
	v_cvt_f32_f16_e32 v56, v166
	v_cvt_f32_f16_sdwa v59, v167 dst_sel:DWORD dst_unused:UNUSED_PAD src0_sel:WORD_1
	v_cvt_f32_f16_e32 v58, v167
	v_cvt_f32_f16_sdwa v61, v168 dst_sel:DWORD dst_unused:UNUSED_PAD src0_sel:WORD_1
	v_cvt_f32_f16_e32 v60, v168
	v_cvt_f32_f16_sdwa v63, v169 dst_sel:DWORD dst_unused:UNUSED_PAD src0_sel:WORD_1
	v_cvt_f32_f16_e32 v62, v169
	v_cvt_f32_f16_sdwa v65, v170 dst_sel:DWORD dst_unused:UNUSED_PAD src0_sel:WORD_1
	v_cvt_f32_f16_e32 v64, v170
	v_cvt_f32_f16_sdwa v67, v171 dst_sel:DWORD dst_unused:UNUSED_PAD src0_sel:WORD_1
	v_cvt_f32_f16_e32 v66, v171
.LBB0_313:
	s_and_b64 vcc, exec, s[42:43]
	v_ashrrev_i32_e32 v199, 31, v198
	s_cbranch_vccnz .LBB0_318
	v_and_b32_e32 v203, 0xffff0000, v3
	v_and_b32_e32 v202, 0xffff0000, v2
	v_and_b32_e32 v209, 0xffff0000, v173
	v_and_b32_e32 v208, 0xffff0000, v172
	v_lshlrev_b32_e32 v201, 16, v3
	v_lshlrev_b32_e32 v200, 16, v2
	v_pk_mul_f32 v[204:205], v[202:203], v[202:203]
	v_lshlrev_b32_e32 v207, 16, v173
	v_lshlrev_b32_e32 v206, 16, v172
	v_pk_mul_f32 v[216:217], v[208:209], v[208:209]
	v_lshlrev_b32_e32 v220, 16, v174
	v_and_b32_e32 v221, 0xffff0000, v174
	v_lshlrev_b32_e32 v230, 16, v175
	v_lshlrev_b32_e32 v224, 16, v176
	v_pk_fma_f32 v[204:205], v[200:201], v[200:201], v[204:205]
	v_pk_fma_f32 v[216:217], v[206:207], v[206:207], v[216:217]
	v_mul_f32_e32 v225, v220, v220
	v_mul_f32_e32 v229, v221, v221
	v_and_b32_e32 v231, 0xffff0000, v175
	v_mul_f32_e32 v0, v230, v230
	v_mov_b32_e32 v228, v224
	v_pk_add_f32 v[204:205], v[204:205], v[204:205] op_sel_hi:[0,1]
	v_pk_add_f32 v[216:217], v[216:217], v[216:217] op_sel_hi:[0,1]
	v_pk_fma_f32 v[238:239], v[230:231], v[230:231], v[0:1] op_sel_hi:[1,1,0]
	v_and_b32_e32 v179, 0xffff0000, v176
	v_lshlrev_b32_e32 v242, 16, v177
	v_and_b32_e32 v243, 0xffff0000, v177
	v_pk_add_f32 v[228:229], v[224:225], v[228:229]
	v_mul_f32_e32 v238, v179, v179
	v_mul_f32_e32 v216, v242, v242
	v_mul_f32_e32 v204, v243, v243
	v_mul_f32_e32 v244, v224, v224
	v_mov_b32_e32 v245, v229
	v_pk_add_f32 v[228:229], v[244:245], v[238:239]
	v_pk_add_f32 v[204:205], v[216:217], v[204:205]
	v_mov_b32_e32 v225, v179
	v_pk_add_f32 v[204:205], v[228:229], v[204:205]
	s_nop 0
	v_add_f32_e32 v0, v204, v205
	v_mov_b32_e32 v204, 0
	v_mov_b32_e32 v205, v202
	v_add_f32_dpp v0, v0, v0 quad_perm:[1,0,3,2] row_mask:0xf bank_mask:0xf bound_ctrl:1
	v_mov_b32_e32 v202, v201
	s_nop 0
	v_add_f32_dpp v0, v0, v0 quad_perm:[2,3,0,1] row_mask:0xf bank_mask:0xf bound_ctrl:1
	s_nop 1
	v_add_f32_dpp v0, v0, v0 row_half_mirror row_mask:0xf bank_mask:0xf bound_ctrl:1
	s_nop 1
	v_add_f32_dpp v0, v0, v0 row_mirror row_mask:0xf bank_mask:0xf bound_ctrl:1
	s_nop 1
	v_mov_b32_dpp v204, v0 row_bcast:15 row_mask:0xa bank_mask:0xf
	v_add_f32_e32 v0, v0, v204
	v_mov_b32_e32 v204, 0
	s_nop 1
	v_mov_b32_dpp v204, v0 row_bcast:31 row_mask:0xc bank_mask:0xf
	v_add_f32_e32 v0, v0, v204
	s_nop 0
	v_readlane_b32 s2, v0, 63
	s_nop 1
	v_fma_f32 v0, s2, v235, v215
	v_mul_f32_e32 v204, 0x4b800000, v0
	v_cmp_gt_f32_e32 vcc, s15, v0
	s_mov_b64 s[2:3], -1
	s_nop 0
	v_cndmask_b32_e32 v0, v0, v204, vcc
	v_rsq_f32_e32 v0, v0
	s_nop 0
	v_mul_f32_e32 v204, 0x45800000, v0
	v_cndmask_b32_e32 v0, v0, v204, vcc
	v_mov_b32_e32 v204, v200
	v_pk_mul_f32 v[200:201], v[108:109], v[202:203]
	v_pk_mul_f32 v[204:205], v[104:105], v[204:205]
	v_pk_fma_f32 v[54:55], v[200:201], v[0:1], v[54:55] op_sel_hi:[1,0,1]
	v_mov_b32_e32 v200, v206
	v_mov_b32_e32 v201, v208
	v_mov_b32_e32 v208, v207
	v_pk_mul_f32 v[200:201], v[100:101], v[200:201]
	v_pk_mul_f32 v[202:203], v[102:103], v[208:209]
	v_pk_fma_f32 v[56:57], v[200:201], v[0:1], v[56:57] op_sel_hi:[1,0,1]
	v_pk_fma_f32 v[58:59], v[202:203], v[0:1], v[58:59] op_sel_hi:[1,0,1]
	v_pk_mul_f32 v[200:201], v[106:107], v[220:221]
	v_pk_mul_f32 v[202:203], v[110:111], v[230:231]
	v_pk_fma_f32 v[60:61], v[200:201], v[0:1], v[60:61] op_sel_hi:[1,0,1]
	v_pk_fma_f32 v[62:63], v[202:203], v[0:1], v[62:63] op_sel_hi:[1,0,1]
	v_pk_mul_f32 v[200:201], v[114:115], v[224:225]
	v_pk_mul_f32 v[202:203], v[112:113], v[242:243]
	v_pk_fma_f32 v[52:53], v[204:205], v[0:1], v[52:53] op_sel_hi:[1,0,1]
	v_pk_fma_f32 v[66:67], v[202:203], v[0:1], v[66:67] op_sel_hi:[1,0,1]
	v_pk_fma_f32 v[64:65], v[200:201], v[0:1], v[64:65] op_sel_hi:[1,0,1]
	s_and_b64 vcc, exec, s[8:9]
	s_cbranch_vccz .LBB0_316
	v_lshlrev_b64 v[200:201], 11, v[198:199]
	v_lshl_add_u64 v[200:201], v[96:97], 0, v[200:201]
	v_cvt_pk_f16_f32 v202, v52, v53
	v_cvt_pk_f16_f32 v203, v54, v55
	global_store_dwordx2 v[200:201], v[202:203], off
	v_cvt_pk_f16_f32 v202, v56, v57
	v_cvt_pk_f16_f32 v203, v58, v59
	global_store_dwordx2 v[200:201], v[202:203], off offset:512
	v_cvt_pk_f16_f32 v202, v60, v61
	v_cvt_pk_f16_f32 v203, v62, v63
	global_store_dwordx2 v[200:201], v[202:203], off offset:1024
	v_cvt_pk_f16_f32 v202, v64, v65
	v_cvt_pk_f16_f32 v203, v66, v67
	global_store_dwordx2 v[200:201], v[202:203], off offset:1536
	s_mov_b64 s[2:3], 0

.LBB0_318:
	s_and_b64 vcc, exec, s[44:45]
	s_cbranch_vccnz .LBB0_320
	v_pk_mul_f32 v[200:201], v[54:55], v[54:55]
	v_pk_mul_f32 v[202:203], v[52:53], v[52:53]
	v_mul_f32_e32 v0, v64, v64
	v_pk_mov_b32 v[204:205], v[202:203], v[200:201] op_sel:[1,0]
	v_mov_b32_e32 v203, v201
	v_pk_add_f32 v[200:201], v[204:205], v[202:203]
	v_pk_mul_f32 v[202:203], v[58:59], v[58:59]
	v_pk_mul_f32 v[204:205], v[56:57], v[56:57]
	v_mul_f32_e32 v179, v65, v65
	v_pk_mov_b32 v[206:207], v[204:205], v[202:203] op_sel:[1,0]
	v_mov_b32_e32 v205, v203
	v_pk_add_f32 v[202:203], v[206:207], v[204:205]
	v_pk_add_f32 v[200:201], v[200:201], v[200:201] op_sel:[0,1] op_sel_hi:[1,0]
	v_pk_add_f32 v[202:203], v[202:203], v[202:203] op_sel:[0,1] op_sel_hi:[1,0]
	v_mov_b32_e32 v201, v0
	v_mov_b32_e32 v203, v179
	v_mul_f32_e32 v0, v61, v61
	v_mul_f32_e32 v204, v66, v66
	v_pk_add_f32 v[200:201], v[200:201], v[202:203]
	v_pk_fma_f32 v[202:203], v[60:61], v[60:61], v[0:1] op_sel_hi:[1,1,0]
	v_mul_f32_e32 v0, v63, v63
	v_mul_f32_e32 v206, v67, v67
	v_mov_b32_e32 v203, v204
	v_pk_fma_f32 v[204:205], v[62:63], v[62:63], v[0:1] op_sel_hi:[1,1,0]
	v_mov_b32_e32 v179, 0
	v_mov_b32_e32 v205, v206
	v_pk_add_f32 v[202:203], v[202:203], v[204:205]
	v_lshlrev_b64 v[198:199], 11, v[198:199]
	v_pk_add_f32 v[200:201], v[200:201], v[202:203]
	v_lshl_add_u64 v[198:199], v[94:95], 0, v[198:199]
	v_add_f32_e32 v0, v200, v201
	s_nop 1
	v_add_f32_dpp v0, v0, v0 quad_perm:[1,0,3,2] row_mask:0xf bank_mask:0xf bound_ctrl:1
	s_nop 1
	v_add_f32_dpp v0, v0, v0 quad_perm:[2,3,0,1] row_mask:0xf bank_mask:0xf bound_ctrl:1
	s_nop 1
	v_add_f32_dpp v0, v0, v0 row_half_mirror row_mask:0xf bank_mask:0xf bound_ctrl:1
	s_nop 1
	v_add_f32_dpp v0, v0, v0 row_mirror row_mask:0xf bank_mask:0xf bound_ctrl:1
	s_nop 1
	v_mov_b32_dpp v179, v0 row_bcast:15 row_mask:0xa bank_mask:0xf
	v_add_f32_e32 v0, v0, v179
	v_mov_b32_e32 v179, 0
	s_nop 1
	v_mov_b32_dpp v179, v0 row_bcast:31 row_mask:0xc bank_mask:0xf
	v_add_f32_e32 v0, v0, v179
	s_nop 0
	v_readlane_b32 s2, v0, 63
	s_nop 1
	v_fma_f32 v0, s2, v235, v215
	v_mul_f32_e32 v179, 0x4b800000, v0
	v_cmp_gt_f32_e32 vcc, s15, v0
	s_nop 1
	v_cndmask_b32_e32 v0, v0, v179, vcc
	v_rsq_f32_e32 v0, v0
	s_nop 0
	v_mul_f32_e32 v179, 0x45800000, v0
	v_cndmask_b32_e32 v0, v0, v179, vcc
	v_pk_mul_f32 v[200:201], v[52:53], v[0:1] op_sel_hi:[1,0]
	v_pk_mul_f32 v[202:203], v[54:55], v[0:1] op_sel_hi:[1,0]
	v_pk_fma_f32 v[200:201], v[120:121], v[200:201], v[20:21]
	v_pk_fma_f32 v[202:203], v[124:125], v[202:203], v[22:23]
	v_cvt_pk_bf16_f32 v200, v200, v201
	s_nop 0
	v_cvt_pk_bf16_f32 v201, v202, v203
	global_store_dwordx2 v[198:199], v[200:201], off
	v_pk_mul_f32 v[200:201], v[56:57], v[0:1] op_sel_hi:[1,0]
	v_pk_mul_f32 v[202:203], v[58:59], v[0:1] op_sel_hi:[1,0]
	v_pk_fma_f32 v[200:201], v[116:117], v[200:201], v[24:25]
	v_pk_fma_f32 v[202:203], v[118:119], v[202:203], v[26:27]
	v_cvt_pk_bf16_f32 v200, v200, v201
	s_nop 0
	v_cvt_pk_bf16_f32 v201, v202, v203
	global_store_dwordx2 v[198:199], v[200:201], off offset:512
	v_pk_mul_f32 v[200:201], v[60:61], v[0:1] op_sel_hi:[1,0]
	v_pk_mul_f32 v[202:203], v[62:63], v[0:1] op_sel_hi:[1,0]
	v_pk_fma_f32 v[200:201], v[122:123], v[200:201], v[28:29]
	v_pk_fma_f32 v[202:203], v[126:127], v[202:203], v[30:31]
	v_cvt_pk_bf16_f32 v200, v200, v201
	s_nop 0
	v_cvt_pk_bf16_f32 v201, v202, v203
	global_store_dwordx2 v[198:199], v[200:201], off offset:1024
	v_pk_mul_f32 v[200:201], v[64:65], v[0:1] op_sel_hi:[1,0]
	v_pk_mul_f32 v[202:203], v[66:67], v[0:1] op_sel_hi:[1,0]
	v_pk_fma_f32 v[200:201], v[130:131], v[200:201], v[32:33]
	v_pk_fma_f32 v[202:203], v[128:129], v[202:203], v[34:35]
	v_cvt_pk_bf16_f32 v200, v200, v201
	s_nop 0
	v_cvt_pk_bf16_f32 v201, v202, v203
	global_store_dwordx2 v[198:199], v[200:201], off offset:1536

; __device__ __forceinline__ void norm_phase(int upd_l, int upd_s, int h_l, int h_s, int xsrc, int xdst, bool dummy, int vc) {
;     ...
;             if (row + 6 * rstep < rend) NP_LOAD(row + 6 * rstep, v2, xb2, yb2);
;             if (row + 3 * rstep < rend) NP_PROC(row + 3 * rstep, v3, xb3, yb3);
.LBB0_324:
	v_lshl_add_u64 v[178:179], v[94:95], 0, v[204:205]
	global_load_dwordx2 v[2:3], v[178:179], off
	global_load_dwordx2 v[172:173], v[178:179], off offset:512
	global_load_dwordx2 v[174:175], v[178:179], off offset:1024
	global_load_dwordx2 v[176:177], v[178:179], off offset:1536
.LBB0_325:
.LBB0_326:
	s_or_b64 exec, exec, s[30:31]
	s_and_saveexec_b64 s[30:31], s[46:47]
	s_cbranch_execz .LBB0_272
	s_or_b64 vcc, s[42:43], s[44:45]
	s_cbranch_vccnz .Lnp_w12_3
	s_waitcnt vmcnt(24)
	s_branch .Lnp_wd_3

.Lnp_wd_3:
	s_and_b64 vcc, exec, s[48:49]
	s_cbranch_vccnz .LBB0_329
	v_cvt_f32_f16_sdwa v69, v190 dst_sel:DWORD dst_unused:UNUSED_PAD src0_sel:WORD_1
	v_cvt_f32_f16_e32 v68, v190
	v_cvt_f32_f16_sdwa v71, v191 dst_sel:DWORD dst_unused:UNUSED_PAD src0_sel:WORD_1
	v_cvt_f32_f16_e32 v70, v191
	v_cvt_f32_f16_sdwa v73, v192 dst_sel:DWORD dst_unused:UNUSED_PAD src0_sel:WORD_1
	v_cvt_f32_f16_e32 v72, v192
	v_cvt_f32_f16_sdwa v75, v193 dst_sel:DWORD dst_unused:UNUSED_PAD src0_sel:WORD_1
	v_cvt_f32_f16_e32 v74, v193
	v_cvt_f32_f16_sdwa v77, v194 dst_sel:DWORD dst_unused:UNUSED_PAD src0_sel:WORD_1
	v_cvt_f32_f16_e32 v76, v194
	v_cvt_f32_f16_sdwa v79, v195 dst_sel:DWORD dst_unused:UNUSED_PAD src0_sel:WORD_1
	v_cvt_f32_f16_e32 v78, v195
	v_cvt_f32_f16_sdwa v81, v180 dst_sel:DWORD dst_unused:UNUSED_PAD src0_sel:WORD_1
	v_cvt_f32_f16_e32 v80, v180
	v_cvt_f32_f16_sdwa v83, v181 dst_sel:DWORD dst_unused:UNUSED_PAD src0_sel:WORD_1
	v_cvt_f32_f16_e32 v82, v181

.LBB0_334:
	s_and_b64 vcc, exec, s[44:45]
	s_cbranch_vccnz .LBB0_272
	v_pk_mul_f32 v[178:179], v[70:71], v[70:71]
	v_pk_mul_f32 v[198:199], v[68:69], v[68:69]
	v_mul_f32_e32 v0, v76, v76
	v_pk_mov_b32 v[200:201], v[198:199], v[178:179] op_sel:[1,0]
	v_mov_b32_e32 v199, v179
	v_pk_add_f32 v[178:179], v[200:201], v[198:199]
	v_pk_mul_f32 v[198:199], v[74:75], v[74:75]
	v_pk_mul_f32 v[200:201], v[72:73], v[72:73]
	v_pk_add_f32 v[178:179], v[178:179], v[178:179] op_sel_hi:[0,1]
	v_pk_mov_b32 v[202:203], v[200:201], v[198:199] op_sel:[1,0]
	v_mov_b32_e32 v201, v199
	v_pk_add_f32 v[198:199], v[202:203], v[200:201]
	v_pk_fma_f32 v[200:201], v[76:77], v[76:77], v[0:1] op_sel_hi:[1,1,0]
	v_mul_f32_e32 v0, v78, v78
	v_pk_add_f32 v[198:199], v[198:199], v[198:199] op_sel_hi:[0,1]
	v_pk_fma_f32 v[202:203], v[78:79], v[78:79], v[0:1] op_sel_hi:[1,1,0]
	v_mul_f32_e32 v200, v80, v80
	v_mul_f32_e32 v202, v81, v81
	v_mul_f32_e32 v198, v82, v82
	v_mul_f32_e32 v178, v83, v83
	v_pk_add_f32 v[200:201], v[200:201], v[202:203]
	v_pk_add_f32 v[178:179], v[198:199], v[178:179]
	s_nop 0
	v_pk_add_f32 v[178:179], v[200:201], v[178:179]
	s_nop 0
	v_add_f32_e32 v0, v178, v179
	v_mov_b32_e32 v178, 0
	s_nop 0
	v_add_f32_dpp v0, v0, v0 quad_perm:[1,0,3,2] row_mask:0xf bank_mask:0xf bound_ctrl:1
	s_nop 1
	v_add_f32_dpp v0, v0, v0 quad_perm:[2,3,0,1] row_mask:0xf bank_mask:0xf bound_ctrl:1
	s_nop 1
	v_add_f32_dpp v0, v0, v0 row_half_mirror row_mask:0xf bank_mask:0xf bound_ctrl:1
	s_nop 1
	v_add_f32_dpp v0, v0, v0 row_mirror row_mask:0xf bank_mask:0xf bound_ctrl:1
	s_nop 1
	v_mov_b32_dpp v178, v0 row_bcast:15 row_mask:0xa bank_mask:0xf
	v_add_f32_e32 v0, v0, v178
	v_mov_b32_e32 v178, 0
	s_nop 1
	v_mov_b32_dpp v178, v0 row_bcast:31 row_mask:0xc bank_mask:0xf
	v_add_f32_e32 v0, v0, v178
	s_nop 0
	v_readlane_b32 s2, v0, 63
	s_nop 1
	v_fma_f32 v0, s2, v235, v215
	v_mul_f32_e32 v178, 0x4b800000, v0
	v_cmp_gt_f32_e32 vcc, s15, v0
	s_nop 1
	v_cndmask_b32_e32 v0, v0, v178, vcc
	v_rsq_f32_e32 v0, v0
	s_nop 0
	v_mul_f32_e32 v178, 0x45800000, v0
	v_cndmask_b32_e32 v0, v0, v178, vcc
	v_pk_mul_f32 v[198:199], v[68:69], v[0:1] op_sel_hi:[1,0]
	v_lshlrev_b64 v[178:179], 11, v[196:197]
	v_pk_mul_f32 v[200:201], v[70:71], v[0:1] op_sel_hi:[1,0]
	v_pk_fma_f32 v[198:199], v[120:121], v[198:199], v[20:21]
	v_lshl_add_u64 v[178:179], v[94:95], 0, v[178:179]
	v_pk_fma_f32 v[200:201], v[124:125], v[200:201], v[22:23]
	v_cvt_pk_bf16_f32 v198, v198, v199
	s_nop 0
	v_cvt_pk_bf16_f32 v199, v200, v201
	global_store_dwordx2 v[178:179], v[198:199], off
	v_pk_mul_f32 v[198:199], v[72:73], v[0:1] op_sel_hi:[1,0]
	v_pk_mul_f32 v[200:201], v[74:75], v[0:1] op_sel_hi:[1,0]
	v_pk_fma_f32 v[198:199], v[116:117], v[198:199], v[24:25]
	v_pk_fma_f32 v[200:201], v[118:119], v[200:201], v[26:27]
	v_cvt_pk_bf16_f32 v198, v198, v199
	s_nop 0
	v_cvt_pk_bf16_f32 v199, v200, v201
	global_store_dwordx2 v[178:179], v[198:199], off offset:512
	v_pk_mul_f32 v[198:199], v[76:77], v[0:1] op_sel_hi:[1,0]
	v_pk_mul_f32 v[200:201], v[78:79], v[0:1] op_sel_hi:[1,0]
	v_pk_fma_f32 v[198:199], v[122:123], v[198:199], v[28:29]
	v_pk_fma_f32 v[200:201], v[126:127], v[200:201], v[30:31]
	v_cvt_pk_bf16_f32 v198, v198, v199
	s_nop 0
	v_cvt_pk_bf16_f32 v199, v200, v201
	global_store_dwordx2 v[178:179], v[198:199], off offset:1024
	v_pk_mul_f32 v[198:199], v[80:81], v[0:1] op_sel_hi:[1,0]
	v_pk_mul_f32 v[200:201], v[82:83], v[0:1] op_sel_hi:[1,0]
	v_pk_fma_f32 v[198:199], v[130:131], v[198:199], v[32:33]
	v_pk_fma_f32 v[200:201], v[128:129], v[200:201], v[34:35]
	v_cvt_pk_bf16_f32 v198, v198, v199
	s_nop 0
	v_cvt_pk_bf16_f32 v199, v200, v201
	global_store_dwordx2 v[178:179], v[198:199], off offset:1536
	s_branch .LBB0_272
.LBB0_336:
	v_lshl_add_u64 v[198:199], v[90:91], 0, v[206:207]
	global_load_dwordx2 v[190:191], v[198:199], off
	global_load_dwordx2 v[192:193], v[198:199], off offset:512
	global_load_dwordx2 v[194:195], v[198:199], off offset:1024
	s_nop 0
	global_load_dwordx2 v[180:181], v[198:199], off offset:1536
	s_cbranch_execnz .LBB0_276

; __device__ __forceinline__ void norm_phase(int upd_l, int upd_s, int h_l, int h_s, int xsrc, int xdst, bool dummy, int vc) {
;     ...
;             if (row + 4 * rstep < rend) NP_LOAD(row + 4 * rstep, v0, xb0, yb0);
.LBB0_338:
	v_lshl_add_u64 v[198:199], v[90:91], 0, v[206:207]
	global_load_dwordx2 v[134:135], v[198:199], off
	global_load_dwordx2 v[136:137], v[198:199], off offset:512
	global_load_dwordx2 v[138:139], v[198:199], off offset:1024
	s_nop 0
	global_load_dwordx2 v[140:141], v[198:199], off offset:1536
	s_cbranch_execnz .LBB0_291

; __device__ __forceinline__ void norm_phase(int upd_l, int upd_s, int h_l, int h_s, int xsrc, int xdst, bool dummy, int vc) {
;     ...
;             if (row + 5 * rstep < rend) NP_LOAD(row + 5 * rstep, v1, xb1, yb1);
.LBB0_340:
	v_lshl_add_u64 v[200:201], v[90:91], 0, v[198:199]
	global_load_dwordx2 v[148:149], v[200:201], off
	global_load_dwordx2 v[150:151], v[200:201], off offset:512
	global_load_dwordx2 v[152:153], v[200:201], off offset:1024
	s_nop 0
	global_load_dwordx2 v[156:157], v[200:201], off offset:1536
	s_cbranch_execnz .LBB0_307

; __device__ __forceinline__ void norm_phase(int upd_l, int upd_s, int h_l, int h_s, int xsrc, int xdst, bool dummy, int vc) {
;     ...
;             if (row + 6 * rstep < rend) NP_LOAD(row + 6 * rstep, v2, xb2, yb2);
.LBB0_342:
	v_lshl_add_u64 v[178:179], v[90:91], 0, v[204:205]
	global_load_dwordx2 v[164:165], v[178:179], off
	global_load_dwordx2 v[166:167], v[178:179], off offset:512
	global_load_dwordx2 v[168:169], v[178:179], off offset:1024
	s_nop 0
	global_load_dwordx2 v[170:171], v[178:179], off offset:1536
	s_cbranch_execnz .LBB0_323
